# diff-attn vector section: far-bias select in an SGPR, rescale threshold kept in a register (4 fewer instructions per key tile)
# baseline (speedup 1.0000x reference)
.LBB0_301:
	s_or_b64 exec, exec, s[2:3]
	s_ashr_i32 s12, s14, 3
	s_ashr_i32 s13, s12, 31
	s_lshl_b64 s[2:3], s[12:13], 13
	s_lshl_b32 s13, s22, 7
	v_and_b32_e32 v4, 31, v159
	s_ashr_i32 s4, s13, 31
	v_and_b32_e32 v0, 63, v159
	s_add_u32 s5, s2, s13
	v_or_b32_e32 v158, s17, v4
	v_lshlrev_b32_e32 v0, 4, v0
	v_or_b32_e32 v146, s5, v158
	v_mov_b64_e32 v[6:7], s[48:49]
	v_add_u32_e32 v162, s16, v0
	s_addc_u32 s14, s3, s4
	v_mad_u64_u32 v[0:1], s[4:5], v146, s53, v[6:7]
	v_mad_i32_i24 v1, s14, v216, v1
	s_lshl_b32 s90, s21, 8
	v_bfe_u32 v5, v159, 5, 1
	v_lshl_add_u64 v[0:1], v[0:1], 0, s[90:91]
	v_lshl_add_u64 v[0:1], s[6:7], 1, v[0:1]
	v_lshlrev_b32_e32 v168, 4, v5
	v_lshl_add_u64 v[8:9], v[0:1], 0, v[168:169]
	global_load_dwordx4 v[112:115], v[8:9], off
	global_load_dwordx4 v[116:119], v[8:9], off offset:32
	global_load_dwordx4 v[120:123], v[8:9], off offset:64
	global_load_dwordx4 v[124:127], v[8:9], off offset:96
	v_ashrrev_i32_e32 v128, 3, v159
	v_ashrrev_i32_e32 v129, 31, v128
	v_ashrrev_i32_e32 v130, 4, v159
	v_mov_b32_e32 v23, v169
	v_ashrrev_i32_e32 v131, 31, v130
	s_or_b32 s23, s13, s17
	v_lshlrev_b32_e32 v157, 2, v5
	v_or_b32_e32 v5, s23, v4
	s_cmpk_gt_i32 s23, 0x627
	v_mov_b32_e32 v147, s14
	v_lshlrev_b32_e32 v8, 4, v159
	v_and_b32_e32 v22, 0x70, v8
	v_lshl_add_u64 v[0:1], s[2:3], 0, v[128:129]
	v_mad_u64_u32 v[2:3], s[4:5], v0, s53, v[6:7]
	v_mad_i32_i24 v3, v1, s53, v3
	v_lshl_add_u64 v[0:1], v[2:3], 0, s[90:91]
	v_lshl_add_u64 v[2:3], v[0:1], 0, v[22:23]
	v_lshl_add_u64 v[0:1], s[2:3], 0, v[130:131]
	v_mad_u64_u32 v[6:7], s[2:3], v0, s53, v[6:7]
	v_mad_i32_i24 v7, v1, s53, v7
	s_movk_i32 s2, 0x90
	v_lshl_add_u64 v[0:1], v[6:7], 0, s[90:91]
	v_and_b32_e32 v6, 0xf0, v8
	v_mov_b32_e32 v7, v169
	v_mul_lo_u32 v23, v128, s2
	s_movk_i32 s2, 0x140
	v_mad_u64_u32 v[132:133], s[2:3], v130, s2, v[6:7]
	v_lshl_add_u64 v[0:1], v[0:1], 0, v[6:7]
	s_movk_i32 s2, 0x1000
	v_add_co_u32_e32 v14, vcc, s2, v0
	s_mov_b32 s2, 0x31000
	s_nop 0
	v_addc_co_u32_e32 v15, vcc, 0, v1, vcc
	global_load_dwordx4 v[6:9], v[2:3], off offset:2048
	global_load_dwordx4 v[10:13], v[2:3], off offset:2176
	v_add_co_u32_e32 v18, vcc, s2, v0
	global_load_dwordx4 v[14:17], v[14:15], off
	s_nop 0
	v_addc_co_u32_e32 v19, vcc, 0, v1, vcc
	global_load_dwordx4 v[18:21], v[18:19], off
	v_add_co_u32_e32 v56, vcc, 0x60000, v2
	s_nop 1
	v_addc_co_u32_e32 v57, vcc, 0, v3, vcc
	global_load_dwordx4 v[48:51], v[56:57], off offset:2048
	global_load_dwordx4 v[52:55], v[56:57], off offset:2176
	v_add3_u32 v163, v23, v22, 0
	s_mov_b32 s2, 0x60000
	v_add_u32_e32 v164, 0, v132
	s_cselect_b64 s[4:5], -1, 0
	s_cmpk_lt_i32 s23, 0x628
	v_sub_u32_e32 v129, v5, v157
	s_waitcnt vmcnt(10)
	ds_write_b128 v228, v[220:223]
	s_mov_b64 s[62:63], exec
	v_cmpx_gt_i32_e32 vcc, 32, v159
	s_nop 1
	ds_write_b128 v228, v[224:227] offset:8192
	s_mov_b64 exec, s[62:63]
	s_waitcnt vmcnt(6)
	ds_write_b128 v162, v[112:115]
	ds_write_b128 v162, v[116:119] offset:1024
	ds_write_b128 v162, v[120:123] offset:2048
	ds_write_b128 v162, v[124:127] offset:3072
	s_waitcnt vmcnt(5)
	ds_write_b128 v163, v[6:9]
	s_waitcnt vmcnt(4)
	ds_write_b128 v163, v[10:13] offset:9216
	s_waitcnt vmcnt(3)
	ds_write_b128 v164, v[14:17] offset:36864
	s_waitcnt vmcnt(2)
	ds_write_b128 v164, v[18:21] offset:47104
	v_readlane_b32 s2, v254, 57
	s_waitcnt vmcnt(1)
	ds_write_b128 v163, v[48:51] offset:18432
	s_waitcnt vmcnt(0)
	ds_write_b128 v163, v[52:55] offset:27648
	s_nop 0
	s_nop 0
	s_nop 0
	s_nop 0
	s_nop 0
	s_nop 0
	s_nop 0
	s_nop 0
	s_nop 0
	s_nop 0
	s_nop 0
	s_nop 0
	s_nop 0
	s_nop 0
	s_nop 0
	s_nop 0
	s_nop 0
	s_nop 0
	s_nop 0
	s_nop 0
	s_nop 0
	s_nop 0
	s_nop 0
	s_nop 0
	s_nop 0
	s_nop 0
	s_nop 0
	s_nop 0
	s_nop 0
	s_nop 0
	s_nop 0
	s_nop 0
	s_nop 0
	s_nop 0
	s_nop 0
	s_nop 0
	s_nop 0
	s_nop 0
	s_nop 0
	s_nop 0
	s_nop 0
	s_nop 0
	s_nop 0
	s_nop 0
	s_nop 0
	s_nop 0
	s_nop 0
	s_nop 0
	s_nop 0
	s_nop 0
	s_nop 0
	s_nop 0
	s_nop 0
	s_nop 0
	v_mov_b32_e32 v6, s2
	s_waitcnt lgkmcnt(0)
	s_barrier
	ds_read_b32 v165, v6
	s_mov_b64 s[2:3], -1
	s_cbranch_scc0 .LBB0_303
	s_add_i32 s2, 0, 0x18000
	v_lshl_add_u32 v5, v129, 2, s2
	ds_read2_b32 v[6:7], v5 offset0:127 offset1:128
	ds_read2_b32 v[8:9], v5 offset0:125 offset1:126
	ds_read2_b32 v[10:11], v5 offset0:119 offset1:120
	ds_read2_b32 v[12:13], v5 offset0:117 offset1:118
	ds_read2_b32 v[14:15], v5 offset0:95 offset1:96
	ds_read2_b32 v[32:33], v5 offset0:93 offset1:94
	ds_read2_b32 v[34:35], v5 offset0:87 offset1:88
	ds_read2_b32 v[36:37], v5 offset0:85 offset1:86
	ds_read2_b32 v[16:17], v5 offset0:111 offset1:112
	ds_read2_b32 v[18:19], v5 offset0:109 offset1:110
	ds_read2_b32 v[20:21], v5 offset0:103 offset1:104
	ds_read2_b32 v[22:23], v5 offset0:101 offset1:102
	ds_read2_b32 v[38:39], v5 offset0:79 offset1:80
	ds_read2_b32 v[40:41], v5 offset0:77 offset1:78
	ds_read2_b32 v[42:43], v5 offset0:71 offset1:72
	ds_read2_b32 v[56:57], v5 offset0:69 offset1:70
	s_mov_b64 s[2:3], 0
	s_waitcnt lgkmcnt(4)
	v_mov_b32_e32 v31, v22
	v_mov_b32_e32 v30, v23
	v_mov_b32_e32 v29, v20
	v_mov_b32_e32 v28, v21
	v_mov_b32_e32 v27, v18
	v_mov_b32_e32 v26, v19
	v_mov_b32_e32 v25, v16
	v_mov_b32_e32 v24, v17
	v_mov_b32_e32 v23, v12
	v_mov_b32_e32 v22, v13
	v_mov_b32_e32 v21, v10
	v_mov_b32_e32 v20, v11
	v_mov_b32_e32 v19, v8
	v_mov_b32_e32 v18, v9
	v_mov_b32_e32 v17, v6
	v_mov_b32_e32 v16, v7
	s_waitcnt lgkmcnt(0)
	v_mov_b32_e32 v46, v57
	v_mov_b32_e32 v45, v42
	v_mov_b32_e32 v44, v43
	v_mov_b32_e32 v43, v40
	v_mov_b32_e32 v42, v41
	v_mov_b32_e32 v41, v38
	v_mov_b32_e32 v40, v39
	v_mov_b32_e32 v39, v36
	v_mov_b32_e32 v38, v37
	v_mov_b32_e32 v37, v34
	v_mov_b32_e32 v36, v35
	v_mov_b32_e32 v35, v32
	v_mov_b32_e32 v34, v33
	v_mov_b32_e32 v33, v14
	v_mov_b32_e32 v32, v15
	v_mov_b32_e32 v47, v56

.LBB0_322:
	v_add_f32_e32 v16, 0, v16
	v_add_f32_e32 v32, 0, v32
	v_add_f32_e32 v16, v17, v16
	v_add_f32_e32 v17, v33, v32
	v_add_f32_e32 v16, v18, v16
	v_add_f32_e32 v17, v34, v17
	v_add_f32_e32 v16, v19, v16
	v_add_f32_e32 v17, v35, v17
	v_add_f32_e32 v16, v20, v16
	v_add_f32_e32 v17, v36, v17
	v_add_f32_e32 v16, v21, v16
	v_add_f32_e32 v17, v37, v17
	v_add_f32_e32 v16, v22, v16
	v_add_f32_e32 v17, v38, v17
	v_add_f32_e32 v16, v23, v16
	v_add_f32_e32 v17, v39, v17
	v_add_f32_e32 v16, v24, v16
	v_add_f32_e32 v17, v40, v17
	v_add_f32_e32 v16, v25, v16
	v_add_f32_e32 v17, v41, v17
	v_add_f32_e32 v16, v26, v16
	v_add_f32_e32 v17, v42, v17
	v_add_f32_e32 v16, v27, v16
	v_add_f32_e32 v17, v43, v17
	v_add_f32_e32 v16, v28, v16
	v_add_f32_e32 v17, v44, v17
	v_add_f32_e32 v16, v29, v16
	v_add_f32_e32 v17, v45, v17
	v_add_f32_e32 v16, v30, v16
	v_add_f32_e32 v17, v46, v17
	v_add_f32_e32 v16, v31, v16
	v_add_f32_e32 v17, v47, v17
	v_add_f32_e32 v16, v16, v17
	v_add_f32_e32 v167, v0, v16
	v_lshrrev_b32_e32 v16, 2, v159
	v_and_or_b32 v16, v16, 3, v157
	s_andn2_b64 vcc, exec, s[2:3]
	v_mul_u32_u24_e32 v168, 0x140, v16
	s_cbranch_vccnz .LBB0_339
	s_add_i32 s2, 0, 0x18000
	v_lshl_add_u32 v190, v129, 2, s2
	v_mul_u32_u24_e32 v16, 0x1800, v130
	v_and_b32_e32 v18, 15, v159
	v_lshl_or_b32 v150, v18, 4, v16
	v_add_u32_e32 v151, 0x30000, v150
	s_mul_i32 s60, s12, 0x3000000
	s_add_u32 s60, s92, s60
	s_addc_u32 s61, s93, 0
	s_add_u32 s60, s60, s90
	s_addc_u32 s61, s61, s91
	s_add_u32 s60, s60, 0xda42000
	s_addc_u32 s61, s61, 0
	v_readlane_b32 s2, v254, 58
	v_lshlrev_b32_e32 v17, 1, v159
	v_and_b32_e32 v18, 3, v159
	v_add_u32_e32 v16, s2, v168
	v_and_b32_e32 v17, 32, v17
	v_lshlrev_b32_e32 v18, 3, v18
	v_add3_u32 v191, v16, v17, v18
	v_mul_u32_u24_e32 v16, 0x1800, v128
	v_and_b32_e32 v18, 7, v159
	v_lshl_or_b32 v16, v18, 4, v16
	v_add_u32_e32 v152, 0x5f800, v16
	v_mov_b64_e32 v[30:31], v[14:15]
	v_mov_b64_e32 v[46:47], v[14:15]
	v_mov_b64_e32 v[62:63], v[14:15]
	v_mov_b64_e32 v[130:131], v[106:107]
	v_mov_b64_e32 v[134:135], v[98:99]
	s_sub_i32 s22, s23, 63
	s_mov_b32 s23, 2
	s_add_i32 s24, s15, 2
	s_mov_b32 s34, 1
	s_or_b32 s14, s15, 1
	s_not_b32 s25, s15
	s_add_i32 s26, s19, s13
	s_mov_b32 s27, 0
	v_mov_b64_e32 v[28:29], v[12:13]
	v_mov_b64_e32 v[26:27], v[10:11]
	v_mov_b64_e32 v[24:25], v[8:9]
	v_mov_b64_e32 v[22:23], v[6:7]
	v_mov_b64_e32 v[20:21], v[4:5]
	v_mov_b64_e32 v[18:19], v[2:3]
	v_mov_b64_e32 v[16:17], v[0:1]
	v_mov_b64_e32 v[44:45], v[12:13]
	v_mov_b64_e32 v[42:43], v[10:11]
	v_mov_b64_e32 v[40:41], v[8:9]
	v_mov_b64_e32 v[38:39], v[6:7]
	v_mov_b64_e32 v[36:37], v[4:5]
	v_mov_b64_e32 v[34:35], v[2:3]
	v_mov_b64_e32 v[32:33], v[0:1]
	v_mov_b64_e32 v[60:61], v[12:13]
	v_mov_b64_e32 v[58:59], v[10:11]
	v_mov_b64_e32 v[56:57], v[8:9]
	v_mov_b64_e32 v[54:55], v[6:7]
	v_mov_b64_e32 v[52:53], v[4:5]
	v_mov_b64_e32 v[50:51], v[2:3]
	v_mov_b64_e32 v[48:49], v[0:1]
	v_mov_b64_e32 v[128:129], v[104:105]
	v_mov_b64_e32 v[132:133], v[96:97]
	v_readfirstlane_b32 s59, v165
	v_add_f32_e32 v212, v149, v171
	s_cmpk_gt_i32 s26, 0x5e8
	s_cselect_b32 s64, s59, 0
	s_cmp_eq_u32 s18, 0
	s_cbranch_scc1 .Lda_entry
	s_barrier
	s_branch .Lda_entry

.Lda_entry:
	v_max3_f32 v148, v64, v65, v66
	v_max3_f32 v154, v72, v73, v74
	v_max3_f32 v155, v80, v81, v82
	v_max3_f32 v170, v88, v89, v90
	v_max3_f32 v148, v148, v67, v68
	v_max3_f32 v154, v154, v75, v76
	v_max3_f32 v155, v155, v83, v84
	v_max3_f32 v170, v170, v91, v92
	v_max3_f32 v148, v148, v69, v70
	v_max3_f32 v154, v154, v77, v78
	v_max3_f32 v155, v155, v85, v86
	v_max3_f32 v170, v170, v93, v94
	v_max_f32_e32 v148, v148, v71
	v_max_f32_e32 v154, v154, v79
	v_max_f32_e32 v155, v155, v87
	v_max_f32_e32 v170, v170, v95
	v_max3_f32 v154, v148, v154, v155
	v_max_f32_e32 v154, v154, v170
	v_mov_b32_e32 v155, v154
	s_mul_hi_u32 s4, s27, 0xaaaaaaab
	s_lshr_b32 s4, s4, 1
	v_permlane32_swap_b32_e32 v155, v154
	v_max_f32_e32 v170, v154, v155
	v_add_f32_e32 v154, s64, v170
	v_cmp_gt_f32_e32 vcc, v154, v212
	s_mov_b32 s58, 0
	s_cbranch_vccz .LBB0_329
	v_max_f32_e32 v154, v154, v154
	v_max_f32_e32 v155, v149, v149
	v_max_f32_e32 v155, v155, v154
	v_sub_f32_e32 v149, v149, v155
	v_exp_f32_e32 v153, v149
	s_mov_b32 s58, 1
	v_mov_b32_e32 v149, v155
	v_add_f32_e32 v212, v155, v171
	v_mul_f32_e32 v167, v167, v153
.LBB0_329:
	v_subrev_f32_e32 v179, s64, v149
	s_mul_i32 s4, s4, 0xf000
	v_subrev_u32_e32 v250, s4, v191
	v_sub_f32_e32 v148, v64, v179
	v_sub_f32_e32 v192, v80, v179
	v_sub_f32_e32 v154, v65, v179
	v_sub_f32_e32 v193, v81, v179
	v_exp_f32_e32 v148, v148
	v_exp_f32_e32 v192, v192
	v_exp_f32_e32 v154, v154
	v_exp_f32_e32 v193, v193
	v_sub_f32_e32 v155, v66, v179
	v_sub_f32_e32 v194, v82, v179
	v_sub_f32_e32 v170, v67, v179
	v_sub_f32_e32 v195, v83, v179
	v_exp_f32_e32 v155, v155
	v_exp_f32_e32 v194, v194
	v_exp_f32_e32 v170, v170
	v_exp_f32_e32 v195, v195
	v_sub_f32_e32 v196, v68, v179
	v_sub_f32_e32 v200, v84, v179
	v_sub_f32_e32 v197, v69, v179
	v_sub_f32_e32 v201, v85, v179
	ds_read_b64_tr_b16 v[128:129], v250 offset:0
	ds_read_b64_tr_b16 v[130:131], v250 offset:2560
	v_exp_f32_e32 v196, v196
	v_exp_f32_e32 v200, v200
	v_exp_f32_e32 v197, v197
	v_exp_f32_e32 v201, v201
	v_sub_f32_e32 v198, v70, v179
	v_sub_f32_e32 v202, v86, v179
	v_sub_f32_e32 v199, v71, v179
	v_sub_f32_e32 v203, v87, v179
	ds_read_b64_tr_b16 v[132:133], v250 offset:64
	ds_read_b64_tr_b16 v[134:135], v250 offset:2624
	v_exp_f32_e32 v198, v198
	v_exp_f32_e32 v202, v202
	v_exp_f32_e32 v199, v199
	v_exp_f32_e32 v203, v203
	v_sub_f32_e32 v204, v72, v179
	v_sub_f32_e32 v208, v88, v179
	v_sub_f32_e32 v205, v73, v179
	v_sub_f32_e32 v209, v89, v179
	ds_read_b64_tr_b16 v[136:137], v250 offset:128
	ds_read_b64_tr_b16 v[138:139], v250 offset:2688
	v_exp_f32_e32 v204, v204
	v_exp_f32_e32 v208, v208
	v_exp_f32_e32 v205, v205
	v_exp_f32_e32 v209, v209
	v_sub_f32_e32 v206, v74, v179
	v_sub_f32_e32 v220, v90, v179
	v_sub_f32_e32 v207, v75, v179
	v_sub_f32_e32 v221, v91, v179
	ds_read_b64_tr_b16 v[140:141], v250 offset:192
	ds_read_b64_tr_b16 v[142:143], v250 offset:2752
	v_exp_f32_e32 v206, v206
	v_exp_f32_e32 v220, v220
	v_exp_f32_e32 v207, v207
	v_exp_f32_e32 v221, v221
	v_sub_f32_e32 v222, v76, v179
	v_sub_f32_e32 v226, v92, v179
	v_sub_f32_e32 v223, v77, v179
	v_sub_f32_e32 v227, v93, v179
	ds_read_b64_tr_b16 v[230:231], v250 offset:5120
	ds_read_b64_tr_b16 v[232:233], v250 offset:7680
	v_exp_f32_e32 v222, v222
	v_exp_f32_e32 v226, v226
	v_exp_f32_e32 v223, v223
	v_exp_f32_e32 v227, v227
	v_sub_f32_e32 v224, v78, v179
	v_sub_f32_e32 v228, v94, v179
	v_sub_f32_e32 v225, v79, v179
	v_sub_f32_e32 v229, v95, v179
	ds_read_b64_tr_b16 v[234:235], v250 offset:5184
	ds_read_b64_tr_b16 v[236:237], v250 offset:7744
	v_exp_f32_e32 v224, v224
	v_exp_f32_e32 v228, v228
	v_exp_f32_e32 v225, v225
	v_exp_f32_e32 v229, v229
	s_barrier
	s_waitcnt vmcnt(0)
	s_cmp_lt_i32 s34, s15
	s_cselect_b64 s[2:3], -1, 0
	s_cbranch_scc0 .Lda_t_skip_stk
	s_bitcmp1_b32 s34, 0
	s_cselect_b32 s12, 0x4800, 0
	v_add_u32_e32 v215, s12, v163
	ds_write_b128 v215, v[96:99]
	ds_write_b128 v215, v[104:107] offset:9216

.Lda_noscale:
	s_add_i32 s23, s23, 1
	s_add_i32 s2, s25, s35
	s_add_i32 s27, s27, 1
	s_sub_i32 s26, s26, 64
	s_cmpk_gt_i32 s26, 0x5e8
	s_cselect_b32 s64, s59, 0
	s_add_u32 s60, s60, s88
	s_addc_u32 s61, s61, s89
	v_add_u32_e32 v164, 0x5000, v164
	v_add_u32_e32 v191, 0x5000, v191
	s_cmp_eq_u32 s2, 1
	s_waitcnt lgkmcnt(0)
	s_barrier
	s_cbranch_scc1 .LBB0_340
	s_mov_b32 s34, s35
	s_branch .LBB0_325

.LBB0_340:
	s_nop 0
	s_cmp_lg_u32 s18, 0
	s_cbranch_scc1 .Lda_exit_b
	s_barrier
